# P1 q/k epilogue: cross-row steps of the per-head sum of squares via v_permlane16_swap / v_permlane32_swap instead of ds_bpermute; on top of the attention MODE 1 epilogue edits
# speedup vs baseline: 1.0029x; 1.0011x over previous
.LBB0_214:
	s_or_b64 exec, exec, s[0:1]
	v_pk_mul_f32 v[202:203], v[174:175], v[174:175]
	v_pk_mul_f32 v[204:205], v[172:173], v[172:173]
	v_and_b32_e32 v201, 64, v223
	v_pk_mov_b32 v[206:207], v[204:205], v[202:203] op_sel:[1,0]
	v_mov_b32_e32 v205, v203
	v_xor_b32_e32 v184, 16, v223
	v_add_u32_e32 v201, 64, v201
	v_pk_add_f32 v[202:203], v[206:207], v[204:205]
	v_pk_mul_f32 v[204:205], v[170:171], v[170:171]
	v_pk_mul_f32 v[206:207], v[168:169], v[168:169]
	v_cmp_lt_i32_e32 vcc, v184, v201
	v_pk_mov_b32 v[208:209], v[206:207], v[204:205] op_sel:[1,0]
	v_mov_b32_e32 v207, v205
	v_cndmask_b32_e32 v184, v223, v184, vcc
	v_pk_add_f32 v[204:205], v[208:209], v[206:207]
	v_lshlrev_b32_e32 v227, 2, v184
	v_mul_f32_e32 v184, v144, v144
	v_mul_f32_e32 v206, v145, v145
	v_pk_add_f32 v[202:203], v[202:203], v[202:203] op_sel:[0,1] op_sel_hi:[1,0]
	v_pk_add_f32 v[204:205], v[204:205], v[204:205] op_sel:[0,1] op_sel_hi:[1,0]
	v_mov_b32_e32 v203, v184
	v_mov_b32_e32 v205, v206
	v_mul_f32_e32 v184, v149, v149
	v_mul_f32_e32 v207, v146, v146
	v_pk_add_f32 v[202:203], v[202:203], v[204:205]
	v_pk_fma_f32 v[204:205], v[148:149], v[148:149], v[184:185] op_sel_hi:[1,1,0]
	v_mul_f32_e32 v184, v151, v151
	v_mul_f32_e32 v208, v147, v147
	v_mov_b32_e32 v205, v207
	v_pk_fma_f32 v[206:207], v[150:151], v[150:151], v[184:185] op_sel_hi:[1,1,0]
	s_nop 0
	v_mov_b32_e32 v207, v208
	v_pk_add_f32 v[204:205], v[204:205], v[206:207]
	s_nop 0
	v_pk_add_f32 v[202:203], v[202:203], v[204:205]
	s_nop 0
	v_add_f32_e32 v184, v202, v203
	v_mov_b32_e32 v202, v184
	v_mov_b32_e32 v255, v184
	s_nop 1
	v_permlane16_swap_b32_e32 v202, v255
	v_xor_b32_e32 v203, 32, v223
	v_cmp_lt_i32_e32 vcc, v203, v201
	s_waitcnt lgkmcnt(0)
	v_add_f32_e32 v184, v202, v255
	v_cndmask_b32_e32 v201, v223, v203, vcc
	v_lshlrev_b32_e32 v228, 2, v201
	v_mov_b32_e32 v201, v184
	v_mov_b32_e32 v255, v184
	s_nop 1
	v_permlane32_swap_b32_e32 v201, v255
	s_waitcnt lgkmcnt(0)
	v_add_f32_e32 v184, v201, v255
	v_fmamk_f32 v184, v184, 0x3c800000, v222
	v_rsq_f32_e32 v202, v184
	s_nop 0
	v_pk_mul_f32 v[204:205], v[172:173], v[202:203] op_sel_hi:[1,0]
	v_pk_mul_f32 v[172:173], v[174:175], v[202:203] op_sel_hi:[1,0]
	s_waitcnt vmcnt(0)
	v_pk_mul_f32 v[174:175], v[124:125], v[204:205]
	v_pk_mul_f32 v[204:205], v[168:169], v[202:203] op_sel_hi:[1,0]
	v_pk_mul_f32 v[168:169], v[170:171], v[202:203] op_sel_hi:[1,0]
	v_pk_mul_f32 v[172:173], v[126:127], v[172:173]
	v_pk_mul_f32 v[168:169], v[122:123], v[168:169]
	v_pk_mul_f32 v[170:171], v[120:121], v[204:205]
	ds_bpermute_b32 v208, v227, v174
	ds_bpermute_b32 v209, v227, v175
	ds_bpermute_b32 v210, v227, v172
	ds_bpermute_b32 v211, v227, v173
	ds_bpermute_b32 v204, v227, v170
	ds_bpermute_b32 v205, v227, v171
	ds_bpermute_b32 v206, v227, v168
	ds_bpermute_b32 v207, v227, v169
	s_and_saveexec_b64 s[0:1], s[6:7]
	s_cbranch_execz .LBB0_216
	s_waitcnt lgkmcnt(0)
	v_pk_mul_f32 v[206:207], v[154:155], v[206:207]
	v_pk_mul_f32 v[204:205], v[152:153], v[204:205]
	v_pk_mul_f32 v[172:173], v[166:167], v[172:173]
	v_pk_mul_f32 v[174:175], v[164:165], v[174:175]
	v_pk_mul_f32 v[210:211], v[162:163], v[210:211]
	v_pk_mul_f32 v[208:209], v[160:161], v[208:209]
	v_pk_mul_f32 v[206:207], v[190:191], v[206:207]
	v_pk_mul_f32 v[204:205], v[188:189], v[204:205]
	v_pk_fma_f32 v[172:173], v[190:191], v[210:211], v[172:173]
	v_pk_fma_f32 v[174:175], v[188:189], v[208:209], v[174:175]
	v_pk_fma_f32 v[168:169], v[158:159], v[168:169], v[206:207]
	v_pk_fma_f32 v[170:171], v[156:157], v[170:171], v[204:205]

.LBB0_218:
	s_lshl_b32 s2, s64, 8
	s_and_b32 s2, s2, 0x100
	v_or_b32_e32 v146, s2, v213
	s_and_b64 s[2:3], s[12:13], exec
	s_mov_b32 s2, 0xde00000
	s_cselect_b32 s2, s2, 0xfe00000
	s_add_u32 s2, s62, s2
	s_addc_u32 s3, s63, 0
	v_lshlrev_b32_e32 v184, 1, v146
	v_lshl_add_u64 v[146:147], s[2:3], 0, v[184:185]
	v_lshlrev_b32_e32 v184, 1, v186
	v_lshl_add_u64 v[146:147], v[146:147], 0, v[184:185]
	v_ashrrev_i32_e32 v149, 31, v148
	v_cndmask_b32_e64 v173, v169, v172, s[4:5]
	v_cndmask_b32_e64 v174, v151, v171, s[4:5]
	v_cndmask_b32_e64 v175, v150, v170, s[4:5]
	v_cndmask_b32_e64 v184, v145, v168, s[4:5]
	v_mov_b32_dpp v203, v174 quad_perm:[1,0,3,2] row_mask:0xf bank_mask:0xf bound_ctrl:1
	v_mov_b32_dpp v201, v175 quad_perm:[1,0,3,2] row_mask:0xf bank_mask:0xf bound_ctrl:1
	v_mov_b32_dpp v184, v184 quad_perm:[1,0,3,2] row_mask:0xf bank_mask:0xf bound_ctrl:1
	v_mov_b32_dpp v173, v173 quad_perm:[1,0,3,2] row_mask:0xf bank_mask:0xf bound_ctrl:1
	v_lshlrev_b64 v[148:149], 10, v[148:149]
	v_lshl_add_u64 v[174:175], v[146:147], 0, v[148:149]
	v_cndmask_b32_e64 v206, v203, v151, s[4:5]
	v_cndmask_b32_e64 v205, v201, v150, s[4:5]
	v_cndmask_b32_e64 v151, v172, v173, s[4:5]
	v_cndmask_b32_e64 v150, v171, v203, s[4:5]
	v_cndmask_b32_e64 v149, v170, v201, s[4:5]
	v_cndmask_b32_e64 v148, v168, v184, s[4:5]
	global_store_dwordx4 v[174:175], v[148:151], off offset:1024
	v_cndmask_b32_e64 v207, v173, v169, s[4:5]
	v_cndmask_b32_e64 v204, v184, v145, s[4:5]
	v_pk_mul_f32 v[148:149], v[110:111], v[110:111]
	v_pk_mul_f32 v[150:151], v[108:109], v[108:109]
	v_mul_f32_e32 v145, v96, v96
	v_pk_mov_b32 v[168:169], v[150:151], v[148:149] op_sel:[1,0]
	v_mov_b32_e32 v151, v149
	v_pk_add_f32 v[148:149], v[168:169], v[150:151]
	v_pk_mul_f32 v[150:151], v[106:107], v[106:107]
	v_pk_mul_f32 v[168:169], v[104:105], v[104:105]
	v_pk_add_f32 v[148:149], v[148:149], v[148:149] op_sel:[0,1] op_sel_hi:[1,0]
	v_pk_mov_b32 v[170:171], v[168:169], v[150:151] op_sel:[1,0]
	v_mov_b32_e32 v169, v151
	v_pk_add_f32 v[150:151], v[170:171], v[168:169]
	v_mul_f32_e32 v168, v97, v97
	v_pk_add_f32 v[150:151], v[150:151], v[150:151] op_sel:[0,1] op_sel_hi:[1,0]
	v_mov_b32_e32 v149, v145
	v_mov_b32_e32 v151, v168
	v_pk_add_f32 v[148:149], v[148:149], v[150:151]
	v_mul_f32_e32 v150, v101, v101
	v_mul_f32_e32 v169, v98, v98
	v_pk_fma_f32 v[150:151], v[100:101], v[100:101], v[150:151] op_sel_hi:[1,1,0]
	v_mul_f32_e32 v168, v103, v103
	v_mul_f32_e32 v170, v99, v99
	v_mov_b32_e32 v151, v169
	v_pk_fma_f32 v[168:169], v[102:103], v[102:103], v[168:169] op_sel_hi:[1,1,0]
	global_store_dwordx4 v[174:175], v[204:207], off
	v_mov_b32_e32 v169, v170
	v_pk_add_f32 v[150:151], v[150:151], v[168:169]
	s_nop 0
	v_pk_add_f32 v[148:149], v[148:149], v[150:151]
	s_nop 0
	v_add_f32_e32 v145, v148, v149
	v_mov_b32_e32 v148, v145
	v_mov_b32_e32 v255, v145
	s_nop 1
	v_permlane16_swap_b32_e32 v148, v255
	s_waitcnt lgkmcnt(0)
	v_add_f32_e32 v145, v148, v255
	v_mov_b32_e32 v148, v145
	v_mov_b32_e32 v255, v145
	s_nop 1
	v_permlane32_swap_b32_e32 v148, v255
	s_waitcnt lgkmcnt(0)
	v_add_f32_e32 v145, v148, v255
	v_fmamk_f32 v145, v145, 0x3c800000, v222
	v_rsq_f32_e32 v148, v145
	s_nop 0
	v_pk_mul_f32 v[150:151], v[108:109], v[148:149] op_sel_hi:[1,0]
	v_pk_mul_f32 v[108:109], v[110:111], v[148:149] op_sel_hi:[1,0]
	v_pk_mul_f32 v[110:111], v[124:125], v[150:151]
	v_pk_mul_f32 v[150:151], v[104:105], v[148:149] op_sel_hi:[1,0]
	v_pk_mul_f32 v[104:105], v[106:107], v[148:149] op_sel_hi:[1,0]
	v_pk_mul_f32 v[108:109], v[126:127], v[108:109]
	v_pk_mul_f32 v[104:105], v[122:123], v[104:105]
	v_pk_mul_f32 v[106:107], v[120:121], v[150:151]
	ds_bpermute_b32 v170, v227, v110
	ds_bpermute_b32 v171, v227, v111
	ds_bpermute_b32 v172, v227, v108
	ds_bpermute_b32 v173, v227, v109
	ds_bpermute_b32 v150, v227, v106
	ds_bpermute_b32 v151, v227, v107
	ds_bpermute_b32 v168, v227, v104
	ds_bpermute_b32 v169, v227, v105
	s_and_saveexec_b64 s[12:13], s[6:7]
	s_cbranch_execz .LBB0_220
	s_waitcnt lgkmcnt(0)
	v_pk_mul_f32 v[168:169], v[130:131], v[168:169]
	v_pk_mul_f32 v[150:151], v[128:129], v[150:151]
	v_pk_mul_f32 v[108:109], v[142:143], v[108:109]
	v_pk_mul_f32 v[110:111], v[140:141], v[110:111]
	v_pk_mul_f32 v[172:173], v[138:139], v[172:173]
	v_pk_mul_f32 v[170:171], v[136:137], v[170:171]
	v_pk_mul_f32 v[168:169], v[190:191], v[168:169]
	v_pk_mul_f32 v[150:151], v[188:189], v[150:151]
	v_pk_fma_f32 v[108:109], v[190:191], v[172:173], v[108:109]
	v_pk_fma_f32 v[110:111], v[188:189], v[170:171], v[110:111]
	v_pk_fma_f32 v[104:105], v[134:135], v[104:105], v[168:169]
	v_pk_fma_f32 v[106:107], v[132:133], v[106:107], v[150:151]

.LBB0_224:
	s_or_b64 exec, exec, s[12:13]
	v_pk_mul_f32 v[96:97], v[94:95], v[94:95]
	v_pk_mul_f32 v[98:99], v[92:93], v[92:93]
	s_nop 0
	v_pk_mov_b32 v[100:101], v[98:99], v[96:97] op_sel:[1,0]
	v_mov_b32_e32 v99, v97
	v_pk_add_f32 v[96:97], v[100:101], v[98:99]
	v_pk_mul_f32 v[98:99], v[90:91], v[90:91]
	v_pk_mul_f32 v[100:101], v[88:89], v[88:89]
	v_pk_add_f32 v[96:97], v[96:97], v[96:97] op_sel:[0,1] op_sel_hi:[1,0]
	v_pk_mov_b32 v[102:103], v[100:101], v[98:99] op_sel:[1,0]
	v_mov_b32_e32 v101, v99
	v_pk_add_f32 v[98:99], v[102:103], v[100:101]
	v_mul_f32_e32 v100, v80, v80
	v_mul_f32_e32 v101, v81, v81
	v_pk_add_f32 v[98:99], v[98:99], v[98:99] op_sel:[0,1] op_sel_hi:[1,0]
	v_mov_b32_e32 v97, v100
	v_mov_b32_e32 v99, v101
	v_pk_add_f32 v[96:97], v[96:97], v[98:99]
	v_mul_f32_e32 v98, v85, v85
	v_mul_f32_e32 v100, v87, v87
	v_mul_f32_e32 v102, v82, v82
	v_mul_f32_e32 v103, v83, v83
	v_pk_fma_f32 v[98:99], v[84:85], v[84:85], v[98:99] op_sel_hi:[1,1,0]
	v_pk_fma_f32 v[100:101], v[86:87], v[86:87], v[100:101] op_sel_hi:[1,1,0]
	v_mov_b32_e32 v99, v102
	v_mov_b32_e32 v101, v103
	v_pk_add_f32 v[98:99], v[98:99], v[100:101]
	s_nop 0
	v_pk_add_f32 v[96:97], v[96:97], v[98:99]
	s_nop 0
	v_add_f32_e32 v96, v96, v97
	v_mov_b32_e32 v97, v96
	v_mov_b32_e32 v255, v96
	s_nop 1
	v_permlane16_swap_b32_e32 v97, v255
	s_waitcnt lgkmcnt(0)
	v_add_f32_e32 v96, v97, v255
	v_mov_b32_e32 v97, v96
	v_mov_b32_e32 v255, v96
	s_nop 1
	v_permlane32_swap_b32_e32 v97, v255
	s_waitcnt lgkmcnt(0)
	v_add_f32_e32 v96, v97, v255
	v_fmamk_f32 v96, v96, 0x3c800000, v222
	v_rsq_f32_e32 v96, v96
	s_nop 0
	v_pk_mul_f32 v[98:99], v[92:93], v[96:97] op_sel_hi:[1,0]
	v_pk_mul_f32 v[92:93], v[94:95], v[96:97] op_sel_hi:[1,0]
	v_pk_mul_f32 v[94:95], v[124:125], v[98:99]
	v_pk_mul_f32 v[98:99], v[88:89], v[96:97] op_sel_hi:[1,0]
	v_pk_mul_f32 v[88:89], v[90:91], v[96:97] op_sel_hi:[1,0]
	v_pk_mul_f32 v[92:93], v[126:127], v[92:93]
	v_pk_mul_f32 v[88:89], v[122:123], v[88:89]
	v_pk_mul_f32 v[90:91], v[120:121], v[98:99]
	ds_bpermute_b32 v102, v227, v94
	ds_bpermute_b32 v103, v227, v95
	ds_bpermute_b32 v104, v227, v92
	ds_bpermute_b32 v105, v227, v93
	ds_bpermute_b32 v98, v227, v90
	ds_bpermute_b32 v99, v227, v91
	ds_bpermute_b32 v100, v227, v88
	ds_bpermute_b32 v101, v227, v89
	s_and_saveexec_b64 s[12:13], s[6:7]
	s_cbranch_execz .LBB0_226
	s_waitcnt vmcnt(7) lgkmcnt(0)
	v_pk_mul_f32 v[100:101], v[154:155], v[100:101]
	v_pk_mul_f32 v[98:99], v[152:153], v[98:99]
	s_waitcnt vmcnt(4)
	v_pk_mul_f32 v[92:93], v[166:167], v[92:93]
	v_pk_mul_f32 v[94:95], v[164:165], v[94:95]
	v_pk_mul_f32 v[104:105], v[162:163], v[104:105]
	v_pk_mul_f32 v[102:103], v[160:161], v[102:103]
	v_pk_mul_f32 v[100:101], v[190:191], v[100:101]
	v_pk_mul_f32 v[98:99], v[188:189], v[98:99]
	v_pk_fma_f32 v[92:93], v[190:191], v[104:105], v[92:93]
	v_pk_fma_f32 v[94:95], v[188:189], v[102:103], v[94:95]
	v_pk_fma_f32 v[88:89], v[158:159], v[88:89], v[100:101]
	v_pk_fma_f32 v[90:91], v[156:157], v[90:91], v[98:99]

.LBB0_228:
	v_cndmask_b32_e64 v88, v82, v90, s[4:5]
	v_pk_mul_f32 v[94:95], v[76:77], v[76:77]
	v_ashrrev_i32_e32 v81, 31, v80
	v_mov_b32_dpp v101, v88 quad_perm:[1,0,3,2] row_mask:0xf bank_mask:0xf bound_ctrl:1
	v_pk_mul_f32 v[88:89], v[78:79], v[78:79]
	v_lshlrev_b64 v[80:81], 10, v[80:81]
	v_pk_mov_b32 v[96:97], v[94:95], v[88:89] op_sel:[1,0]
	v_mov_b32_e32 v95, v89
	v_pk_add_f32 v[88:89], v[96:97], v[94:95]
	v_pk_mul_f32 v[94:95], v[74:75], v[74:75]
	v_pk_mul_f32 v[96:97], v[72:73], v[72:73]
	v_pk_add_f32 v[88:89], v[88:89], v[88:89] op_sel:[0,1] op_sel_hi:[1,0]
	v_pk_mov_b32 v[98:99], v[96:97], v[94:95] op_sel:[1,0]
	v_mov_b32_e32 v97, v95
	v_pk_add_f32 v[94:95], v[98:99], v[96:97]
	v_mul_f32_e32 v96, v64, v64
	v_mul_f32_e32 v97, v65, v65
	v_pk_add_f32 v[94:95], v[94:95], v[94:95] op_sel:[0,1] op_sel_hi:[1,0]
	v_mov_b32_e32 v89, v96
	v_mov_b32_e32 v95, v97
	v_pk_add_f32 v[88:89], v[88:89], v[94:95]
	v_mul_f32_e32 v94, v69, v69
	v_mul_f32_e32 v96, v71, v71
	v_mul_f32_e32 v98, v66, v66
	v_mul_f32_e32 v99, v67, v67
	v_pk_fma_f32 v[94:95], v[68:69], v[68:69], v[94:95] op_sel_hi:[1,1,0]
	v_pk_fma_f32 v[96:97], v[70:71], v[70:71], v[96:97] op_sel_hi:[1,1,0]
	v_mov_b32_e32 v95, v98
	v_mov_b32_e32 v97, v99
	v_pk_add_f32 v[94:95], v[94:95], v[96:97]
	v_cndmask_b32_e64 v87, v85, v86, s[4:5]
	v_pk_add_f32 v[88:89], v[88:89], v[94:95]
	v_lshl_add_u64 v[94:95], v[146:147], 0, v[80:81]
	v_add_f32_e32 v88, v88, v89
	v_mov_b32_e32 v89, v88
	v_mov_b32_e32 v255, v88
	s_nop 1
	v_permlane16_swap_b32_e32 v89, v255
	v_cndmask_b32_e64 v93, v84, v92, s[4:5]
	v_cndmask_b32_e64 v100, v83, v91, s[4:5]
	v_mov_b32_dpp v87, v87 quad_perm:[1,0,3,2] row_mask:0xf bank_mask:0xf bound_ctrl:1
	v_mov_b32_dpp v97, v93 quad_perm:[1,0,3,2] row_mask:0xf bank_mask:0xf bound_ctrl:1
	s_waitcnt lgkmcnt(0)
	v_add_f32_e32 v88, v89, v255
	v_mov_b32_e32 v89, v88
	v_mov_b32_e32 v255, v88
	s_nop 1
	v_permlane32_swap_b32_e32 v89, v255
	v_mov_b32_dpp v96, v100 quad_perm:[1,0,3,2] row_mask:0xf bank_mask:0xf bound_ctrl:1
	v_cndmask_b32_e64 v85, v87, v85, s[4:5]
	v_cndmask_b32_e64 v84, v97, v84, s[4:5]
	v_cndmask_b32_e64 v83, v96, v83, s[4:5]
	s_waitcnt lgkmcnt(0)
	v_add_f32_e32 v80, v89, v255
	v_fmamk_f32 v80, v80, 0x3c800000, v222
	v_rsq_f32_e32 v80, v80
	v_cndmask_b32_e64 v82, v101, v82, s[4:5]
	global_store_dwordx4 v[94:95], v[82:85], off
	v_cndmask_b32_e64 v93, v86, v87, s[4:5]
	v_cndmask_b32_e64 v92, v92, v97, s[4:5]
	v_pk_mul_f32 v[82:83], v[76:77], v[80:81] op_sel_hi:[1,0]
	v_pk_mul_f32 v[76:77], v[78:79], v[80:81] op_sel_hi:[1,0]
	v_pk_mul_f32 v[78:79], v[124:125], v[82:83]
	v_pk_mul_f32 v[82:83], v[72:73], v[80:81] op_sel_hi:[1,0]
	v_pk_mul_f32 v[72:73], v[74:75], v[80:81] op_sel_hi:[1,0]
	v_pk_mul_f32 v[76:77], v[126:127], v[76:77]
	v_pk_mul_f32 v[72:73], v[122:123], v[72:73]
	v_pk_mul_f32 v[74:75], v[120:121], v[82:83]
	ds_bpermute_b32 v86, v227, v78
	ds_bpermute_b32 v87, v227, v79
	ds_bpermute_b32 v88, v227, v76
	ds_bpermute_b32 v89, v227, v77
	ds_bpermute_b32 v82, v227, v74
	ds_bpermute_b32 v83, v227, v75
	ds_bpermute_b32 v84, v227, v72
	ds_bpermute_b32 v85, v227, v73
	v_cndmask_b32_e64 v91, v91, v96, s[4:5]
	v_cndmask_b32_e64 v90, v90, v101, s[4:5]
	global_store_dwordx4 v[94:95], v[90:93], off offset:1024
	s_and_saveexec_b64 s[12:13], s[6:7]
	s_cbranch_execz .LBB0_230
	s_waitcnt vmcnt(4) lgkmcnt(0)
	v_pk_mul_f32 v[84:85], v[130:131], v[84:85]
	v_pk_mul_f32 v[82:83], v[128:129], v[82:83]
	v_pk_mul_f32 v[76:77], v[142:143], v[76:77]
	v_pk_mul_f32 v[78:79], v[140:141], v[78:79]
	s_waitcnt vmcnt(3)
	v_pk_mul_f32 v[88:89], v[138:139], v[88:89]
	v_pk_mul_f32 v[86:87], v[136:137], v[86:87]
	v_pk_mul_f32 v[84:85], v[190:191], v[84:85]
	v_pk_mul_f32 v[82:83], v[188:189], v[82:83]
	v_pk_fma_f32 v[76:77], v[190:191], v[88:89], v[76:77]
	v_pk_fma_f32 v[78:79], v[188:189], v[86:87], v[78:79]
	s_waitcnt vmcnt(2)
	v_pk_fma_f32 v[72:73], v[134:135], v[72:73], v[84:85]
	v_pk_fma_f32 v[74:75], v[132:133], v[74:75], v[82:83]

.LBB0_234:
	s_or_b64 exec, exec, s[12:13]
	v_pk_mul_f32 v[64:65], v[62:63], v[62:63]
	v_pk_mul_f32 v[66:67], v[60:61], v[60:61]
	s_nop 0
	v_pk_mov_b32 v[68:69], v[66:67], v[64:65] op_sel:[1,0]
	v_mov_b32_e32 v67, v65
	v_pk_add_f32 v[64:65], v[68:69], v[66:67]
	v_pk_mul_f32 v[66:67], v[58:59], v[58:59]
	v_pk_mul_f32 v[68:69], v[56:57], v[56:57]
	v_pk_add_f32 v[64:65], v[64:65], v[64:65] op_sel:[0,1] op_sel_hi:[1,0]
	v_pk_mov_b32 v[70:71], v[68:69], v[66:67] op_sel:[1,0]
	v_mov_b32_e32 v69, v67
	v_pk_add_f32 v[66:67], v[70:71], v[68:69]
	v_mul_f32_e32 v68, v48, v48
	v_mul_f32_e32 v69, v49, v49
	v_pk_add_f32 v[66:67], v[66:67], v[66:67] op_sel:[0,1] op_sel_hi:[1,0]
	v_mov_b32_e32 v65, v68
	v_mov_b32_e32 v67, v69
	v_pk_add_f32 v[64:65], v[64:65], v[66:67]
	v_mul_f32_e32 v66, v53, v53
	v_mul_f32_e32 v68, v55, v55
	v_mul_f32_e32 v70, v50, v50
	v_mul_f32_e32 v71, v51, v51
	v_pk_fma_f32 v[66:67], v[52:53], v[52:53], v[66:67] op_sel_hi:[1,1,0]
	v_pk_fma_f32 v[68:69], v[54:55], v[54:55], v[68:69] op_sel_hi:[1,1,0]
	v_mov_b32_e32 v67, v70
	v_mov_b32_e32 v69, v71
	v_pk_add_f32 v[66:67], v[66:67], v[68:69]
	s_nop 0
	v_pk_add_f32 v[64:65], v[64:65], v[66:67]
	s_nop 0
	v_add_f32_e32 v64, v64, v65
	v_mov_b32_e32 v65, v64
	v_mov_b32_e32 v255, v64
	s_nop 1
	v_permlane16_swap_b32_e32 v65, v255
	s_waitcnt lgkmcnt(0)
	v_add_f32_e32 v64, v65, v255
	v_mov_b32_e32 v65, v64
	v_mov_b32_e32 v255, v64
	s_nop 1
	v_permlane32_swap_b32_e32 v65, v255
	s_waitcnt lgkmcnt(0)
	v_add_f32_e32 v64, v65, v255
	v_fmamk_f32 v64, v64, 0x3c800000, v222
	v_rsq_f32_e32 v64, v64
	s_nop 0
	v_pk_mul_f32 v[66:67], v[60:61], v[64:65] op_sel_hi:[1,0]
	v_pk_mul_f32 v[60:61], v[62:63], v[64:65] op_sel_hi:[1,0]
	v_pk_mul_f32 v[62:63], v[124:125], v[66:67]
	v_pk_mul_f32 v[66:67], v[56:57], v[64:65] op_sel_hi:[1,0]
	v_pk_mul_f32 v[56:57], v[58:59], v[64:65] op_sel_hi:[1,0]
	v_pk_mul_f32 v[60:61], v[126:127], v[60:61]
	v_pk_mul_f32 v[56:57], v[122:123], v[56:57]
	v_pk_mul_f32 v[58:59], v[120:121], v[66:67]
	ds_bpermute_b32 v70, v227, v62
	ds_bpermute_b32 v71, v227, v63
	ds_bpermute_b32 v72, v227, v60
	ds_bpermute_b32 v73, v227, v61
	ds_bpermute_b32 v66, v227, v58
	ds_bpermute_b32 v67, v227, v59
	ds_bpermute_b32 v68, v227, v56
	ds_bpermute_b32 v69, v227, v57
	s_and_saveexec_b64 s[12:13], s[6:7]
	s_cbranch_execz .LBB0_236
	s_waitcnt vmcnt(7) lgkmcnt(0)
	v_pk_mul_f32 v[68:69], v[154:155], v[68:69]
	v_pk_mul_f32 v[66:67], v[152:153], v[66:67]
	s_waitcnt vmcnt(4)
	v_pk_mul_f32 v[60:61], v[166:167], v[60:61]
	v_pk_mul_f32 v[62:63], v[164:165], v[62:63]
	v_pk_mul_f32 v[72:73], v[162:163], v[72:73]
	v_pk_mul_f32 v[70:71], v[160:161], v[70:71]
	v_pk_mul_f32 v[68:69], v[190:191], v[68:69]
	v_pk_mul_f32 v[66:67], v[188:189], v[66:67]
	v_pk_fma_f32 v[60:61], v[190:191], v[72:73], v[60:61]
	v_pk_fma_f32 v[62:63], v[188:189], v[70:71], v[62:63]
	v_pk_fma_f32 v[56:57], v[158:159], v[56:57], v[68:69]
	v_pk_fma_f32 v[58:59], v[156:157], v[58:59], v[66:67]

.LBB0_238:
	v_cndmask_b32_e64 v56, v50, v58, s[4:5]
	v_pk_mul_f32 v[62:63], v[44:45], v[44:45]
	v_ashrrev_i32_e32 v49, 31, v48
	v_mov_b32_dpp v69, v56 quad_perm:[1,0,3,2] row_mask:0xf bank_mask:0xf bound_ctrl:1
	v_pk_mul_f32 v[56:57], v[46:47], v[46:47]
	v_lshlrev_b64 v[48:49], 10, v[48:49]
	v_pk_mov_b32 v[64:65], v[62:63], v[56:57] op_sel:[1,0]
	v_mov_b32_e32 v63, v57
	v_pk_add_f32 v[56:57], v[64:65], v[62:63]
	v_pk_mul_f32 v[62:63], v[42:43], v[42:43]
	v_pk_mul_f32 v[64:65], v[40:41], v[40:41]
	v_pk_add_f32 v[56:57], v[56:57], v[56:57] op_sel:[0,1] op_sel_hi:[1,0]
	v_pk_mov_b32 v[66:67], v[64:65], v[62:63] op_sel:[1,0]
	v_mov_b32_e32 v65, v63
	v_pk_add_f32 v[62:63], v[66:67], v[64:65]
	v_mul_f32_e32 v64, v32, v32
	v_mul_f32_e32 v65, v33, v33
	v_pk_add_f32 v[62:63], v[62:63], v[62:63] op_sel:[0,1] op_sel_hi:[1,0]
	v_mov_b32_e32 v57, v64
	v_mov_b32_e32 v63, v65
	v_pk_add_f32 v[56:57], v[56:57], v[62:63]
	v_mul_f32_e32 v62, v37, v37
	v_mul_f32_e32 v64, v39, v39
	v_mul_f32_e32 v66, v34, v34
	v_mul_f32_e32 v67, v35, v35
	v_pk_fma_f32 v[62:63], v[36:37], v[36:37], v[62:63] op_sel_hi:[1,1,0]
	v_pk_fma_f32 v[64:65], v[38:39], v[38:39], v[64:65] op_sel_hi:[1,1,0]
	v_mov_b32_e32 v63, v66
	v_mov_b32_e32 v65, v67
	v_pk_add_f32 v[62:63], v[62:63], v[64:65]
	v_cndmask_b32_e64 v55, v53, v54, s[4:5]
	v_pk_add_f32 v[56:57], v[56:57], v[62:63]
	v_lshl_add_u64 v[62:63], v[146:147], 0, v[48:49]
	v_add_f32_e32 v56, v56, v57
	v_mov_b32_e32 v57, v56
	v_mov_b32_e32 v255, v56
	s_nop 1
	v_permlane16_swap_b32_e32 v57, v255
	v_cndmask_b32_e64 v61, v52, v60, s[4:5]
	v_cndmask_b32_e64 v68, v51, v59, s[4:5]
	v_mov_b32_dpp v55, v55 quad_perm:[1,0,3,2] row_mask:0xf bank_mask:0xf bound_ctrl:1
	v_mov_b32_dpp v65, v61 quad_perm:[1,0,3,2] row_mask:0xf bank_mask:0xf bound_ctrl:1
	s_waitcnt lgkmcnt(0)
	v_add_f32_e32 v56, v57, v255
	v_mov_b32_e32 v57, v56
	v_mov_b32_e32 v255, v56
	s_nop 1
	v_permlane32_swap_b32_e32 v57, v255
	v_mov_b32_dpp v64, v68 quad_perm:[1,0,3,2] row_mask:0xf bank_mask:0xf bound_ctrl:1
	v_cndmask_b32_e64 v53, v55, v53, s[4:5]
	v_cndmask_b32_e64 v52, v65, v52, s[4:5]
	v_cndmask_b32_e64 v51, v64, v51, s[4:5]
	s_waitcnt lgkmcnt(0)
	v_add_f32_e32 v48, v57, v255
	v_fmamk_f32 v48, v48, 0x3c800000, v222
	v_rsq_f32_e32 v48, v48
	v_cndmask_b32_e64 v50, v69, v50, s[4:5]
	global_store_dwordx4 v[62:63], v[50:53], off
	v_cndmask_b32_e64 v61, v54, v55, s[4:5]
	v_cndmask_b32_e64 v60, v60, v65, s[4:5]
	v_pk_mul_f32 v[50:51], v[44:45], v[48:49] op_sel_hi:[1,0]
	v_pk_mul_f32 v[44:45], v[46:47], v[48:49] op_sel_hi:[1,0]
	v_pk_mul_f32 v[46:47], v[124:125], v[50:51]
	v_pk_mul_f32 v[50:51], v[40:41], v[48:49] op_sel_hi:[1,0]
	v_pk_mul_f32 v[40:41], v[42:43], v[48:49] op_sel_hi:[1,0]
	v_pk_mul_f32 v[44:45], v[126:127], v[44:45]
	v_pk_mul_f32 v[40:41], v[122:123], v[40:41]
	v_pk_mul_f32 v[42:43], v[120:121], v[50:51]
	ds_bpermute_b32 v54, v227, v46
	ds_bpermute_b32 v55, v227, v47
	ds_bpermute_b32 v56, v227, v44
	ds_bpermute_b32 v57, v227, v45
	ds_bpermute_b32 v50, v227, v42
	ds_bpermute_b32 v51, v227, v43
	ds_bpermute_b32 v52, v227, v40
	ds_bpermute_b32 v53, v227, v41
	v_cndmask_b32_e64 v59, v59, v64, s[4:5]
	v_cndmask_b32_e64 v58, v58, v69, s[4:5]
	global_store_dwordx4 v[62:63], v[58:61], off offset:1024
	s_and_saveexec_b64 s[12:13], s[6:7]
	s_cbranch_execz .LBB0_240
	s_waitcnt vmcnt(5) lgkmcnt(0)
	v_pk_mul_f32 v[52:53], v[130:131], v[52:53]
	v_pk_mul_f32 v[50:51], v[128:129], v[50:51]
	s_waitcnt vmcnt(2)
	v_pk_mul_f32 v[44:45], v[142:143], v[44:45]
	v_pk_mul_f32 v[46:47], v[140:141], v[46:47]
	v_pk_mul_f32 v[56:57], v[138:139], v[56:57]
	v_pk_mul_f32 v[54:55], v[136:137], v[54:55]
	v_pk_mul_f32 v[52:53], v[190:191], v[52:53]
	v_pk_mul_f32 v[50:51], v[188:189], v[50:51]
	v_pk_fma_f32 v[44:45], v[190:191], v[56:57], v[44:45]
	v_pk_fma_f32 v[46:47], v[188:189], v[54:55], v[46:47]
	v_pk_fma_f32 v[40:41], v[134:135], v[40:41], v[52:53]
	v_pk_fma_f32 v[42:43], v[132:133], v[42:43], v[50:51]

.LBB0_244:
	s_or_b64 exec, exec, s[12:13]
	v_pk_mul_f32 v[32:33], v[30:31], v[30:31]
	v_pk_mul_f32 v[34:35], v[28:29], v[28:29]
	s_nop 0
	v_pk_mov_b32 v[36:37], v[34:35], v[32:33] op_sel:[1,0]
	v_mov_b32_e32 v35, v33
	v_pk_add_f32 v[32:33], v[36:37], v[34:35]
	v_pk_mul_f32 v[34:35], v[26:27], v[26:27]
	v_pk_mul_f32 v[36:37], v[24:25], v[24:25]
	v_pk_add_f32 v[32:33], v[32:33], v[32:33] op_sel:[0,1] op_sel_hi:[1,0]
	v_pk_mov_b32 v[38:39], v[36:37], v[34:35] op_sel:[1,0]
	v_mov_b32_e32 v37, v35
	v_pk_add_f32 v[34:35], v[38:39], v[36:37]
	v_mul_f32_e32 v36, v16, v16
	v_mul_f32_e32 v37, v17, v17
	v_pk_add_f32 v[34:35], v[34:35], v[34:35] op_sel:[0,1] op_sel_hi:[1,0]
	v_mov_b32_e32 v33, v36
	v_mov_b32_e32 v35, v37
	v_pk_add_f32 v[32:33], v[32:33], v[34:35]
	v_mul_f32_e32 v34, v21, v21
	v_mul_f32_e32 v36, v23, v23
	v_mul_f32_e32 v38, v18, v18
	v_mul_f32_e32 v39, v19, v19
	v_pk_fma_f32 v[34:35], v[20:21], v[20:21], v[34:35] op_sel_hi:[1,1,0]
	v_pk_fma_f32 v[36:37], v[22:23], v[22:23], v[36:37] op_sel_hi:[1,1,0]
	v_mov_b32_e32 v35, v38
	v_mov_b32_e32 v37, v39
	v_pk_add_f32 v[34:35], v[34:35], v[36:37]
	s_nop 0
	v_pk_add_f32 v[32:33], v[32:33], v[34:35]
	s_nop 0
	v_add_f32_e32 v32, v32, v33
	v_mov_b32_e32 v33, v32
	v_mov_b32_e32 v255, v32
	s_nop 1
	v_permlane16_swap_b32_e32 v33, v255
	s_waitcnt lgkmcnt(0)
	v_add_f32_e32 v32, v33, v255
	v_mov_b32_e32 v33, v32
	v_mov_b32_e32 v255, v32
	s_nop 1
	v_permlane32_swap_b32_e32 v33, v255
	s_waitcnt lgkmcnt(0)
	v_add_f32_e32 v32, v33, v255
	v_fmamk_f32 v32, v32, 0x3c800000, v222
	v_rsq_f32_e32 v32, v32
	s_nop 0
	v_pk_mul_f32 v[34:35], v[28:29], v[32:33] op_sel_hi:[1,0]
	v_pk_mul_f32 v[28:29], v[30:31], v[32:33] op_sel_hi:[1,0]
	v_pk_mul_f32 v[30:31], v[124:125], v[34:35]
	v_pk_mul_f32 v[34:35], v[24:25], v[32:33] op_sel_hi:[1,0]
	v_pk_mul_f32 v[24:25], v[26:27], v[32:33] op_sel_hi:[1,0]
	v_pk_mul_f32 v[28:29], v[126:127], v[28:29]
	v_pk_mul_f32 v[24:25], v[122:123], v[24:25]
	v_pk_mul_f32 v[26:27], v[120:121], v[34:35]
	ds_bpermute_b32 v38, v227, v30
	ds_bpermute_b32 v39, v227, v31
	ds_bpermute_b32 v40, v227, v28
	ds_bpermute_b32 v41, v227, v29
	ds_bpermute_b32 v34, v227, v26
	ds_bpermute_b32 v35, v227, v27
	ds_bpermute_b32 v36, v227, v24
	ds_bpermute_b32 v37, v227, v25
	s_and_saveexec_b64 s[12:13], s[6:7]
	s_cbranch_execz .LBB0_246
	s_waitcnt vmcnt(7) lgkmcnt(0)
	v_pk_mul_f32 v[36:37], v[154:155], v[36:37]
	v_pk_mul_f32 v[34:35], v[152:153], v[34:35]
	s_waitcnt vmcnt(4)
	v_pk_mul_f32 v[28:29], v[166:167], v[28:29]
	v_pk_mul_f32 v[30:31], v[164:165], v[30:31]
	v_pk_mul_f32 v[40:41], v[162:163], v[40:41]
	v_pk_mul_f32 v[38:39], v[160:161], v[38:39]
	v_pk_mul_f32 v[36:37], v[190:191], v[36:37]
	v_pk_mul_f32 v[34:35], v[188:189], v[34:35]
	v_pk_fma_f32 v[28:29], v[190:191], v[40:41], v[28:29]
	v_pk_fma_f32 v[30:31], v[188:189], v[38:39], v[30:31]
	v_pk_fma_f32 v[24:25], v[158:159], v[24:25], v[36:37]
	v_pk_fma_f32 v[26:27], v[156:157], v[26:27], v[34:35]

.LBB0_248:
	v_cndmask_b32_e64 v24, v18, v26, s[4:5]
	v_pk_mul_f32 v[30:31], v[12:13], v[12:13]
	v_ashrrev_i32_e32 v17, 31, v16
	v_mov_b32_dpp v37, v24 quad_perm:[1,0,3,2] row_mask:0xf bank_mask:0xf bound_ctrl:1
	v_pk_mul_f32 v[24:25], v[14:15], v[14:15]
	v_lshlrev_b64 v[16:17], 10, v[16:17]
	v_pk_mov_b32 v[32:33], v[30:31], v[24:25] op_sel:[1,0]
	v_mov_b32_e32 v31, v25
	v_pk_add_f32 v[24:25], v[32:33], v[30:31]
	v_pk_mul_f32 v[30:31], v[10:11], v[10:11]
	v_pk_mul_f32 v[32:33], v[8:9], v[8:9]
	v_pk_add_f32 v[24:25], v[24:25], v[24:25] op_sel:[0,1] op_sel_hi:[1,0]
	v_pk_mov_b32 v[34:35], v[32:33], v[30:31] op_sel:[1,0]
	v_mov_b32_e32 v33, v31
	v_pk_add_f32 v[30:31], v[34:35], v[32:33]
	v_mul_f32_e32 v32, v0, v0
	v_mul_f32_e32 v33, v1, v1
	v_pk_add_f32 v[30:31], v[30:31], v[30:31] op_sel:[0,1] op_sel_hi:[1,0]
	v_mov_b32_e32 v25, v32
	v_mov_b32_e32 v31, v33
	v_pk_add_f32 v[24:25], v[24:25], v[30:31]
	v_mul_f32_e32 v30, v5, v5
	v_mul_f32_e32 v32, v7, v7
	v_mul_f32_e32 v34, v2, v2
	v_mul_f32_e32 v35, v3, v3
	v_pk_fma_f32 v[30:31], v[4:5], v[4:5], v[30:31] op_sel_hi:[1,1,0]
	v_pk_fma_f32 v[32:33], v[6:7], v[6:7], v[32:33] op_sel_hi:[1,1,0]
	v_mov_b32_e32 v31, v34
	v_mov_b32_e32 v33, v35
	v_pk_add_f32 v[30:31], v[30:31], v[32:33]
	v_cndmask_b32_e64 v23, v21, v22, s[4:5]
	v_pk_add_f32 v[24:25], v[24:25], v[30:31]
	v_lshl_add_u64 v[30:31], v[146:147], 0, v[16:17]
	v_add_f32_e32 v24, v24, v25
	v_mov_b32_e32 v25, v24
	v_mov_b32_e32 v255, v24
	s_nop 1
	v_permlane16_swap_b32_e32 v25, v255
	v_cndmask_b32_e64 v29, v20, v28, s[4:5]
	v_cndmask_b32_e64 v36, v19, v27, s[4:5]
	v_mov_b32_dpp v23, v23 quad_perm:[1,0,3,2] row_mask:0xf bank_mask:0xf bound_ctrl:1
	v_mov_b32_dpp v33, v29 quad_perm:[1,0,3,2] row_mask:0xf bank_mask:0xf bound_ctrl:1
	s_waitcnt lgkmcnt(0)
	v_add_f32_e32 v24, v25, v255
	v_mov_b32_e32 v25, v24
	v_mov_b32_e32 v255, v24
	s_nop 1
	v_permlane32_swap_b32_e32 v25, v255
	v_mov_b32_dpp v32, v36 quad_perm:[1,0,3,2] row_mask:0xf bank_mask:0xf bound_ctrl:1
	v_cndmask_b32_e64 v21, v23, v21, s[4:5]
	v_cndmask_b32_e64 v20, v33, v20, s[4:5]
	v_cndmask_b32_e64 v19, v32, v19, s[4:5]
	s_waitcnt lgkmcnt(0)
	v_add_f32_e32 v16, v25, v255
	v_fmamk_f32 v16, v16, 0x3c800000, v222
	v_rsq_f32_e32 v16, v16
	v_cndmask_b32_e64 v18, v37, v18, s[4:5]
	global_store_dwordx4 v[30:31], v[18:21], off
	v_cndmask_b32_e64 v29, v22, v23, s[4:5]
	v_cndmask_b32_e64 v28, v28, v33, s[4:5]
	v_pk_mul_f32 v[18:19], v[12:13], v[16:17] op_sel_hi:[1,0]
	v_pk_mul_f32 v[12:13], v[14:15], v[16:17] op_sel_hi:[1,0]
	v_pk_mul_f32 v[14:15], v[124:125], v[18:19]
	v_pk_mul_f32 v[18:19], v[8:9], v[16:17] op_sel_hi:[1,0]
	v_pk_mul_f32 v[8:9], v[10:11], v[16:17] op_sel_hi:[1,0]
	v_pk_mul_f32 v[12:13], v[126:127], v[12:13]
	v_pk_mul_f32 v[8:9], v[122:123], v[8:9]
	v_pk_mul_f32 v[10:11], v[120:121], v[18:19]
	ds_bpermute_b32 v22, v227, v14
	ds_bpermute_b32 v23, v227, v15
	ds_bpermute_b32 v24, v227, v12
	ds_bpermute_b32 v25, v227, v13
	ds_bpermute_b32 v18, v227, v10
	ds_bpermute_b32 v19, v227, v11
	ds_bpermute_b32 v20, v227, v8
	ds_bpermute_b32 v21, v227, v9
	v_cndmask_b32_e64 v27, v27, v32, s[4:5]
	v_cndmask_b32_e64 v26, v26, v37, s[4:5]
	global_store_dwordx4 v[30:31], v[26:29], off offset:1024
	s_and_saveexec_b64 s[12:13], s[6:7]
	s_cbranch_execz .LBB0_250
	s_waitcnt vmcnt(4) lgkmcnt(0)
	v_pk_mul_f32 v[20:21], v[130:131], v[20:21]
	v_pk_mul_f32 v[18:19], v[128:129], v[18:19]
	v_pk_mul_f32 v[12:13], v[142:143], v[12:13]
	v_pk_mul_f32 v[14:15], v[140:141], v[14:15]
	s_waitcnt vmcnt(3)
	v_pk_mul_f32 v[24:25], v[138:139], v[24:25]
	v_pk_mul_f32 v[22:23], v[136:137], v[22:23]
	v_pk_mul_f32 v[20:21], v[190:191], v[20:21]
	v_pk_mul_f32 v[18:19], v[188:189], v[18:19]
	v_pk_fma_f32 v[12:13], v[190:191], v[24:25], v[12:13]
	v_pk_fma_f32 v[14:15], v[188:189], v[22:23], v[14:15]
	s_waitcnt vmcnt(2)
	v_pk_fma_f32 v[8:9], v[134:135], v[8:9], v[20:21]
	v_pk_fma_f32 v[10:11], v[132:133], v[10:11], v[18:19]

	.amdhsa_kernel _Z9hymba_fwd4Args
		.amdhsa_group_segment_fixed_size 0
		.amdhsa_private_segment_fixed_size 0
		.amdhsa_kernarg_size 456
		.amdhsa_user_sgpr_count 2
		.amdhsa_user_sgpr_dispatch_ptr 0
		.amdhsa_user_sgpr_queue_ptr 0
		.amdhsa_user_sgpr_kernarg_segment_ptr 1
		.amdhsa_user_sgpr_dispatch_id 0
		.amdhsa_user_sgpr_kernarg_preload_length 0
		.amdhsa_user_sgpr_kernarg_preload_offset 0
		.amdhsa_user_sgpr_private_segment_size 0
		.amdhsa_uses_dynamic_stack 0
		.amdhsa_enable_private_segment 0
		.amdhsa_system_sgpr_workgroup_id_x 1
		.amdhsa_system_sgpr_workgroup_id_y 0
		.amdhsa_system_sgpr_workgroup_id_z 0
		.amdhsa_system_sgpr_workgroup_info 0
		.amdhsa_system_vgpr_workitem_id 2
		.amdhsa_next_free_vgpr 256
		.amdhsa_next_free_sgpr 102
		.amdhsa_accum_offset 256
		.amdhsa_reserve_vcc 1
		.amdhsa_float_round_mode_32 0
		.amdhsa_float_round_mode_16_64 0
		.amdhsa_float_denorm_mode_32 3
		.amdhsa_float_denorm_mode_16_64 3
		.amdhsa_dx10_clamp 1
		.amdhsa_ieee_mode 1
		.amdhsa_fp16_overflow 0
		.amdhsa_tg_split 0
		.amdhsa_exception_fp_ieee_invalid_op 0
		.amdhsa_exception_fp_denorm_src 0
		.amdhsa_exception_fp_ieee_div_zero 0
		.amdhsa_exception_fp_ieee_overflow 0
		.amdhsa_exception_fp_ieee_underflow 0
		.amdhsa_exception_fp_ieee_inexact 0
		.amdhsa_exception_int_div_zero 0
	.end_amdhsa_kernel

amdhsa.kernels:
  - .agpr_count:     0
    .args:
      - .offset:         0
        .size:           200
        .value_kind:     by_value
      - .offset:         200
        .size:           4
        .value_kind:     hidden_block_count_x
      - .offset:         204
        .size:           4
        .value_kind:     hidden_block_count_y
      - .offset:         208
        .size:           4
        .value_kind:     hidden_block_count_z
      - .offset:         212
        .size:           2
        .value_kind:     hidden_group_size_x
      - .offset:         214
        .size:           2
        .value_kind:     hidden_group_size_y
      - .offset:         216
        .size:           2
        .value_kind:     hidden_group_size_z
      - .offset:         218
        .size:           2
        .value_kind:     hidden_remainder_x
      - .offset:         220
        .size:           2
        .value_kind:     hidden_remainder_y
      - .offset:         222
        .size:           2
        .value_kind:     hidden_remainder_z
      - .offset:         240
        .size:           8
        .value_kind:     hidden_global_offset_x
      - .offset:         248
        .size:           8
        .value_kind:     hidden_global_offset_y
      - .offset:         256
        .size:           8
        .value_kind:     hidden_global_offset_z
      - .offset:         264
        .size:           2
        .value_kind:     hidden_grid_dims
      - .offset:         288
        .size:           8
        .value_kind:     hidden_multigrid_sync_arg
      - .offset:         320
        .size:           4
        .value_kind:     hidden_dynamic_lds_size
    .group_segment_fixed_size: 0
    .kernarg_segment_align: 8
    .kernarg_segment_size: 456
    .language:       OpenCL C
    .language_version:
      - 2
      - 0
    .max_flat_workgroup_size: 512
    .name:           _Z9hymba_fwd4Args
    .private_segment_fixed_size: 0
    .sgpr_count:     108
    .sgpr_spill_count: 32
    .symbol:         _Z9hymba_fwd4Args.kd
    .uniform_work_group_size: 1
    .uses_dynamic_stack: false
    .vgpr_count:     256
    .vgpr_spill_count: 0
    .wavefront_size: 64
